# team-local barriers (4 WGs sharing row panels) replace grid barriers at GEMM-GEMM seams 1,6,9
# speedup vs baseline: 1.0052x; 1.0052x over previous
; #define LAS __attribute__((address_space(3)))
; __global__ void __launch_bounds__(NWAVES * 64, 2) mk_fwd(Args a) {
;     ...
;     unsigned char* ws = a.ws;
;     bf16* WGU1 = (bf16*)(ws + WS_WGU1); bf16* WD1 = (bf16*)(ws + WS_WD1); bf16* WIN = (bf16*)(ws + WS_WIN);
;     bf16* WOA = (bf16*)(ws + WS_WOA); bf16* WOB = (bf16*)(ws + WS_WOB); bf16* WO = (bf16*)(ws + WS_WO);
;     bf16* WGU2 = (bf16*)(ws + WS_WGU2); bf16* WD2 = (bf16*)(ws + WS_WD2); bf16* WPG = (bf16*)(ws + WS_WPG); bf16* WPP = (bf16*)(ws + WS_WPP);
;     bf16* PWT = (bf16*)(ws + WS_PWT); bf16* SGW = (bf16*)(ws + WS_SGW); float* PART = (float*)(ws + WS_PART); bf16* PB = (bf16*)(ws + WS_PB);
;     bf16* S0 = (bf16*)(ws + WS_SLAB); bf16* S1 = (bf16*)(ws + WS_SLAB + SLAB); bf16* S2 = (bf16*)(ws + WS_SLAB + 2 * SLAB);
;     bf16* S3 = (bf16*)(ws + WS_SLAB + 3 * SLAB); bf16* S4 = (bf16*)(ws + WS_SLAB + 4 * SLAB); bf16* S5 = (bf16*)(ws + WS_SLAB + 5 * SLAB);
;     bf16* XN = S0; bf16* ACT = S1; bf16* FB = S4;
;     float* RS = (float*)(ws + WS_RS); bf16* HB = S0;
;     bf16* BB = (bf16*)a.out;
;     const int lo = a.ph_lo, hi = a.ph_hi;
;     ...
;     if (tid < 2) ((LAS unsigned*)(lds + MISC_OFF))[tid] = 0u;
;     __syncthreads();
;     XcdBarrier xbar; xbar.bar = (unsigned*)(ws + WS_CTL); xbar.x = 0; xbar.st = nullptr;
;     if (hi - lo > 1) xbar = xcd_barrier_post((unsigned*)(ws + WS_CTL), (volatile LAS unsigned*)(lds + MISC_OFF));
;     ...
;     if (lo < 0) cg::this_grid().sync();
;     if (IN(0)) {
;         LAS float* scr = (LAS float*)(lds + wave * 16384);
;         constexpr int NITEMS = 13312;
;         for (int it = gw; it < NITEMS; it += NGW) {
;             int r = it;
;             if (transpose_mat<true>(r, a.in[I_F1G], D, FF, WGU1, 0, a.in[I_F1PRE], scr, lane)) continue;
;             if (transpose_mat<true>(r, a.in[I_F1U], D, FF, WGU1, 1, a.in[I_F1PRE], scr, lane)) continue;
;             if (transpose_mat<false>(r, a.in[I_F1D], FF, D, WD1, -1, nullptr, scr, lane)) continue;
;             if (transpose_mat<true>(r, a.in[I_WIN], D, DIN, WIN, -1, a.in[I_MIXPRE], scr, lane)) continue;
;             if (transpose_mat<false>(r, a.in[I_WOA], D, D, WOA, -1, nullptr, scr, lane)) continue;
;             if (transpose_mat<false>(r, a.in[I_WOB], D, D, WOB, -1, nullptr, scr, lane)) continue;
.LBB0_19:
	s_getreg_b32 s100, hwreg(HW_REG_XCC_ID, 0, 4)
	s_mov_b32 s99, 0
	v_cmp_eq_u32_e32 vcc, 0, v195
	s_and_saveexec_b64 s[4:5], vcc
	s_cbranch_execz .Ltm_init_done
	s_and_b32 s98, s2, 7
	s_lshl_b32 s98, s98, 3
	s_bfe_u32 s101, s2, 0x30003
	s_or_b32 s98, s98, s101
	s_lshl_b32 s98, s98, 5
	s_lshr_b32 s101, s2, 6
	s_lshl_b32 s101, s101, 2
	s_add_u32 s98, s98, s101
	s_add_u32 s6, s28, 0x3903600
	s_addc_u32 s7, s29, 0
	s_and_b32 s101, s100, 15
	s_add_u32 s101, s101, 1
	v_mov_b32_e32 v1, s98
	v_mov_b32_e32 v2, s101
	global_store_dword v1, v2, s[6:7] offset:16
.Ltm_init_done:
	s_or_b64 exec, exec, s[4:5]
	s_lshr_b32 s78, s3, 6
	s_lshl_b32 s3, s2, 3
	s_add_i32 s79, s78, s3
	s_add_u32 s6, s28, 0xb00000
	s_addc_u32 s7, s29, 0
	s_add_u32 s10, s28, 0x1100000
	s_addc_u32 s11, s29, 0
	s_add_u32 s4, s28, 0x1b00000
	s_addc_u32 s5, s29, 0
	s_load_dwordx16 s[12:27], s[0:1], 0x80
	v_writelane_b32 v254, s4, 0
	s_load_dwordx16 s[52:67], s[0:1], 0x0
	s_load_dwordx16 s[36:51], s[0:1], 0x40
	v_writelane_b32 v254, s5, 1
	s_add_u32 s4, s28, 0x1d00000
	s_addc_u32 s5, s29, 0
	v_writelane_b32 v254, s4, 2
	v_and_b32_e32 v194, 63, v195
	s_nop 0
	v_writelane_b32 v254, s5, 3
	s_add_u32 s4, s28, 0x1f00000
	s_addc_u32 s5, s29, 0
	v_writelane_b32 v254, s4, 4
	s_nop 1
	v_writelane_b32 v254, s5, 5
	s_add_u32 s4, s28, 0x2100000
	s_addc_u32 s5, s29, 0
	v_writelane_b32 v254, s4, 6
	s_nop 1
	v_writelane_b32 v254, s5, 7
	s_add_u32 s4, s28, 0x2c00000
	s_addc_u32 s5, s29, 0
	s_add_u32 s86, s28, 0x3200000
	s_addc_u32 s87, s29, 0
	s_add_u32 s88, s28, 0x3400000
	v_writelane_b32 v254, s4, 8
	s_addc_u32 s89, s29, 0
	s_nop 0
	v_writelane_b32 v254, s5, 9
	s_add_u32 s4, s28, 0x3500000
	s_addc_u32 s5, s29, 0
	v_writelane_b32 v254, s4, 10
	s_add_u32 s90, s28, 0x3a00000
	s_addc_u32 s91, s29, 0
	v_writelane_b32 v254, s5, 11
	s_waitcnt lgkmcnt(0)
	v_writelane_b32 v254, s12, 12
	s_add_u32 s34, s28, 0x5000000
	s_addc_u32 s35, s29, 0
	v_writelane_b32 v254, s13, 13
	v_writelane_b32 v254, s14, 14
	v_writelane_b32 v254, s15, 15
	v_writelane_b32 v254, s16, 16
	v_writelane_b32 v254, s17, 17
	v_writelane_b32 v254, s18, 18
	v_writelane_b32 v254, s19, 19
	v_writelane_b32 v254, s20, 20
	v_writelane_b32 v254, s21, 21
	s_add_u32 s92, s28, 0x3910000
	v_writelane_b32 v254, s22, 22
	s_addc_u32 s93, s29, 0
	v_writelane_b32 v254, s23, 23
	s_cmp_lt_i32 s30, 1
	v_writelane_b32 v254, s24, 24
	s_cselect_b64 s[4:5], -1, 0
	s_cmp_gt_i32 s31, 0
	v_writelane_b32 v254, s25, 25
	s_cselect_b64 s[8:9], -1, 0
	v_writelane_b32 v254, s26, 26
	v_writelane_b32 v254, s27, 27
	s_and_b64 s[0:1], s[4:5], s[8:9]
	v_writelane_b32 v254, s0, 28
	s_andn2_b64 vcc, exec, s[0:1]
	s_nop 0
	v_writelane_b32 v254, s1, 29
	s_cbranch_vccnz .LBB0_162
	v_writelane_b32 v254, s6, 30
	s_cmpk_gt_i32 s79, 0x33ff
	s_nop 0
	v_writelane_b32 v254, s7, 31
	v_writelane_b32 v254, s10, 32
	s_nop 1
	v_writelane_b32 v254, s11, 33
	v_writelane_b32 v254, s86, 34
	s_nop 1
	v_writelane_b32 v254, s87, 35
	v_writelane_b32 v254, s90, 36
	s_nop 1
	v_writelane_b32 v254, s91, 37
	v_writelane_b32 v254, s88, 38
	s_nop 1
	v_writelane_b32 v254, s89, 39
	v_writelane_b32 v254, s84, 40
	s_nop 1
	v_writelane_b32 v254, s85, 41
	v_writelane_b32 v254, s83, 42
	v_writelane_b32 v254, s82, 43
	v_writelane_b32 v254, s80, 44
	s_nop 1
	v_writelane_b32 v254, s81, 45
	v_writelane_b32 v254, s78, 46
	v_writelane_b32 v254, s79, 47
	s_cbranch_scc1 .LBB0_99
	v_readlane_b32 s0, v254, 46
	s_lshl_b32 s0, s0, 14
	v_lshrrev_b32_e32 v34, 5, v194
	v_and_b32_e32 v30, 31, v195
	s_add_i32 s0, s0, 0
	v_lshlrev_b32_e32 v0, 2, v30
	v_mul_u32_u24_e32 v2, 0x84, v34
	v_add3_u32 v35, s0, v0, v2
	v_lshlrev_b32_e32 v0, 3, v195
	v_lshrrev_b32_e32 v36, 3, v194
	v_and_b32_e32 v0, 56, v0
	v_mul_u32_u24_e32 v4, 0x84, v0
	v_lshlrev_b32_e32 v5, 2, v36
	v_add3_u32 v37, s0, v4, v5
	v_readlane_b32 s0, v254, 30
	v_mov_b32_e32 v1, 0
	v_lshlrev_b32_e32 v0, 1, v0
	v_readlane_b32 s1, v254, 31
	s_lshl_b32 s3, s33, 3
	v_lshl_add_u64 v[2:3], s[28:29], 0, v[0:1]
	v_lshl_add_u64 v[4:5], s[0:1], 0, v[0:1]
	v_readlane_b32 s0, v254, 32
	v_readlane_b32 s1, v254, 33
	v_or_b32_e32 v38, 8, v36
	v_or_b32_e32 v39, 16, v36
	v_lshl_add_u64 v[6:7], s[0:1], 0, v[0:1]
	v_readlane_b32 s0, v254, 0
	v_readlane_b32 s1, v254, 1
	v_or_b32_e32 v40, 24, v36
	s_movk_i32 s25, 0x5000
	v_lshl_add_u64 v[8:9], s[0:1], 0, v[0:1]
	v_readlane_b32 s0, v254, 2
	v_readlane_b32 s1, v254, 3
	s_mov_b32 s94, 0x16000
	s_mov_b32 s96, 0x1b000
	v_lshl_add_u64 v[10:11], s[0:1], 0, v[0:1]
	v_readlane_b32 s0, v254, 4
	v_readlane_b32 s1, v254, 5
	s_mov_b32 s95, 0x21000
	s_mov_b32 s26, 0x26000
	v_lshl_add_u64 v[12:13], s[0:1], 0, v[0:1]
	v_readlane_b32 s0, v254, 6
	v_readlane_b32 s1, v254, 7
	s_mov_b32 s7, 0x2c000
	s_mov_b32 s97, 0x31000
	v_lshl_add_u64 v[14:15], s[0:1], 0, v[0:1]
	v_readlane_b32 s0, v254, 8
	v_readlane_b32 s1, v254, 9
	s_mov_b32 s11, 0x37000
	s_mov_b32 s24, 0x3c000
	v_lshl_add_u64 v[16:17], s[0:1], 0, v[0:1]
	v_readlane_b32 s0, v254, 34
	v_readlane_b32 s1, v254, 35
	s_mov_b32 s6, 0x42000
	s_mov_b32 s5, 0x47000
	v_lshl_add_u64 v[18:19], s[0:1], 0, v[0:1]
	v_readlane_b32 s0, v254, 38
	v_readlane_b32 s1, v254, 39
	s_mov_b32 s4, 0x4d000
	s_mov_b32 s10, 0x52000
	v_lshl_add_u64 v[20:21], s[0:1], 0, v[0:1]
	v_readlane_b32 s0, v254, 10
	v_readlane_b32 s1, v254, 11
	s_mov_b32 s8, 0x58000
	v_add_u32_e32 v41, 0x400, v35
	v_lshl_add_u64 v[22:23], s[0:1], 0, v[0:1]
	s_add_u32 s0, s44, 0x40000
	s_addc_u32 s1, s45, 0
	v_writelane_b32 v254, s0, 48
	v_lshlrev_b32_e32 v0, 2, v30
	v_add_u32_e32 v42, 0x800, v35
	v_writelane_b32 v254, s1, 49
	s_mov_b64 s[0:1], 0x3520000
	v_lshl_add_u64 v[24:25], v[2:3], 0, s[0:1]
	s_add_u32 s0, s44, 0x80000
	s_addc_u32 s1, s45, 0
	v_writelane_b32 v254, s0, 50
	v_add_u32_e32 v43, 0xc00, v35
	v_add_u32_e32 v44, 0x1000, v35
	v_writelane_b32 v254, s1, 51
	s_mov_b64 s[0:1], 0x3540000
	v_lshl_add_u64 v[26:27], v[2:3], 0, s[0:1]
	s_add_u32 s0, s44, 0xc0000
	s_addc_u32 s1, s45, 0
	v_writelane_b32 v254, s0, 52
	s_lshl_b32 s21, s33, 8
	s_lshl_b32 s23, s33, 9
	v_writelane_b32 v254, s1, 53
	s_mov_b64 s[0:1], 0x3560000
	v_readlane_b32 s12, v254, 47
	v_lshl_add_u64 v[28:29], v[2:3], 0, s[0:1]
	s_lshl_b32 s20, s12, 5
	s_lshl_b32 s22, s12, 6
	s_mov_b32 s0, 0xb000
	s_mov_b32 s1, 0x10000
	v_add_u32_e32 v45, 0x1400, v35
	v_add_u32_e32 v46, 0x1800, v35
	v_add_u32_e32 v47, 0x1c00, v35
	s_branch .LBB0_23

; __global__ void __launch_bounds__(NWAVES * 64, 2) mk_fwd(Args a) {
;     ...
;     if (IN(1)) { pg8::Gemm g{XN, WGU1, M, 2 * FF, D}; pg8::StaticOrder S; S.init(M, 2 * FF, G, bid); EpiGU E{ACT, RS, lds}; rs_table_fill(lds, S, RS);
;         pg8::gemm_phase<EpiGU, pg8::StaticOrder, ALIGN_GU, true, NT_WIDE, ZZ, PEELK>(lds, g, S, E); }
.LBB0_212:
	s_and_b32 s98, s2, 7
	s_lshl_b32 s98, s98, 3
	s_bfe_u32 s101, s2, 0x30003
	s_or_b32 s98, s98, s101
	s_lshl_b32 s98, s98, 5
	s_add_u32 s4, s28, 0x3903600
	s_addc_u32 s5, s29, 0
	v_mov_b32_e32 v0, s98
	global_load_dwordx4 v[0:3], v0, s[4:5] offset:16 sc1
	s_waitcnt vmcnt(0)
	v_readfirstlane_b32 s98, v0
	v_readfirstlane_b32 s101, v1
	s_cmp_eq_u32 s98, s101
	s_cselect_b32 s99, 1, 0
	v_readfirstlane_b32 s101, v2
	s_cmp_eq_u32 s98, s101
	s_cselect_b32 s4, 1, 0
	s_and_b32 s99, s99, s4
	v_readfirstlane_b32 s101, v3
	s_cmp_eq_u32 s98, s101
	s_cselect_b32 s4, 1, 0
	s_and_b32 s99, s99, s4
	s_cmp_lg_u32 s98, 0
	s_cselect_b32 s4, 1, 0
	s_and_b32 s99, s99, s4
	s_cmp_lt_i32 s30, 2
	s_cselect_b64 s[4:5], -1, 0
	s_add_u32 s16, s28, 0x9000000
	s_addc_u32 s17, s29, 0
	s_and_b64 s[12:13], s[4:5], s[0:1]
	s_andn2_b64 vcc, exec, s[12:13]
	s_cbranch_vccnz .LBB0_257
	s_mov_b32 s14, -1
	s_ashr_i32 s3, s2, 31
	s_mov_b32 s15, s14
	s_ashr_i32 s8, s33, 31
	s_waitcnt vmcnt(15)
	v_mov_b64_e32 v[0:1], 0xb00
	v_mov_b64_e32 v[2:3], 0xaff
	s_movk_i32 s24, 0x161
	s_mov_b64 s[20:21], s[2:3]
	s_mov_b32 s9, s14
	s_mov_b64 s[18:19], s[14:15]
	s_branch .LBB0_216

; __device__ __forceinline__ unsigned xb_ld(unsigned* p)              { return __hip_atomic_load(p, __ATOMIC_RELAXED, __HIP_MEMORY_SCOPE_AGENT); }
; __device__ __forceinline__ unsigned xb_add(unsigned* p, unsigned v) { return __hip_atomic_fetch_add(p, v, __ATOMIC_RELAXED, __HIP_MEMORY_SCOPE_AGENT); }
; #define XB_SPIN(cond, bar) do { unsigned _sp = 0; while (cond) { __builtin_amdgcn_s_sleep(1); \
;     if ((++_sp & 255u) == 0u) { if (xb_ld(&(bar)[XB_TMO])) break; if (_sp > XB_SPIN_CAP) { atomicAdd(&(bar)[XB_TMO], 1u); break; } } } } while (0)
; __device__ __forceinline__ void xcd_barrier(const XcdBarrier& b) {
;     asm volatile("s_waitcnt vmcnt(0)" ::: "memory");
;     __syncthreads();
;     if (threadIdx.x == 0) {
;         unsigned* bar = b.bar;
;         __builtin_amdgcn_s_waitcnt(0);
;         unsigned nloc = b.st[0], nx = b.st[1];
;         if (nloc == 0u) { xcd_barrier_complete(bar, b.x, nloc, nx); b.st[0] = nloc; b.st[1] = nx; }
;         const unsigned old = xb_add(&bar[XB_XSUB(b.x)], 1u);
;         const unsigned gen = old / nloc;
;         if (old + 1u == (gen + 1u) * nloc) {
;             __builtin_amdgcn_fence(__ATOMIC_RELEASE, "agent");
;             asm volatile("s_waitcnt vmcnt(0)" ::: "memory");
;             const unsigned og = xb_add(&bar[XB_TOP], 1u);
;             const unsigned tg = og / nx;
;             if (og + 1u == (tg + 1u) * nx) xb_add(&bar[XB_TOPGEN], 1u);
;             else XB_SPIN(xb_ld(&bar[XB_TOPGEN]) == tg, bar);
;             __builtin_amdgcn_fence(__ATOMIC_ACQUIRE, "agent");
;             xb_add(&bar[XB_XGEN(b.x)], 1u);
;             asm volatile("s_waitcnt vmcnt(0)" ::: "memory");
;         } else {
;             XB_SPIN(xb_ld(&bar[XB_XGEN(b.x)]) == gen, bar);
;             __builtin_amdgcn_fence(__ATOMIC_ACQUIRE, "agent");
;             asm volatile("s_waitcnt vmcnt(0)" ::: "memory");
;         }
;     }
;     __syncthreads();
; }
.LBB0_257:
	s_cmp_gt_i32 s31, 2
	s_cselect_b64 s[0:1], -1, 0
	s_and_b64 s[4:5], s[12:13], s[0:1]
	s_andn2_b64 vcc, exec, s[4:5]
	s_cbranch_vccnz .LBB0_307
	s_waitcnt vmcnt(0)
	s_barrier
	v_cmp_eq_u32_e32 vcc, 0, v195
	s_and_saveexec_b64 s[4:5], vcc
	s_cbranch_execz .Ltb307_done
	s_cmp_eq_u32 s99, 1
	s_cbranch_scc1 .Ltb307_fast
	buffer_wbl2 sc1
	s_waitcnt vmcnt(0)
.Ltb307_fast:
	s_and_b32 s3, s2, 7
	s_lshl_b32 s3, s3, 3
	s_bfe_u32 s13, s2, 0x30003
	s_or_b32 s3, s3, s13
	s_lshl_b32 s3, s3, 5
	s_add_u32 s8, s28, 0x3903600
	s_addc_u32 s9, s29, 0
	v_mov_b32_e32 v0, s3
	v_mov_b32_e32 v1, 1
	global_atomic_add v2, v0, v1, s[8:9] sc0
	s_waitcnt vmcnt(0)
	v_and_b32_e32 v2, -4, v2
	v_add_u32_e32 v2, 4, v2
	s_mov_b32 s15, 0
.Ltb307_spin:
	global_load_dword v3, v0, s[8:9] sc1
	s_waitcnt vmcnt(0)
	v_cmp_ge_u32_e32 vcc, v3, v2
	s_cbranch_vccnz .Ltb307_rel
	s_sleep 1
	s_add_u32 s15, s15, 1
	s_cmp_lt_u32 s15, 0x200000
	s_cbranch_scc1 .Ltb307_spin
.Ltb307_rel:
	buffer_inv sc1
	s_waitcnt vmcnt(0)
.Ltb307_done:
	s_or_b64 exec, exec, s[4:5]
	s_barrier
.LBB0_307:
	s_cmp_lt_i32 s30, 3
	s_cselect_b64 s[4:5], -1, 0
	s_add_u32 s20, s28, 0x3700000
	s_addc_u32 s21, s29, 0
	s_add_u32 s18, s28, 0x15000000
	s_addc_u32 s19, s29, 0
	s_and_b64 s[12:13], s[4:5], s[0:1]
	s_andn2_b64 vcc, exec, s[12:13]
	s_cbranch_vccnz .LBB0_336
	s_cmpk_gt_i32 s2, 0x1ff
	v_readfirstlane_b32 s4, v195
	s_cbranch_scc1 .LBB0_336
	s_ashr_i32 s3, s2, 31
	s_lshr_b32 s0, s3, 29
	s_add_i32 s5, s2, s0
	s_and_b32 s0, s5, -8
	s_sub_i32 s8, s2, s0
	s_cmp_gt_i32 s8, -1
	s_cbranch_scc0 .LBB0_311
	s_lshl_b32 s9, s8, 6
	s_cbranch_execz .LBB0_312
	s_branch .LBB0_313

; __device__ __forceinline__ unsigned xb_ld(unsigned* p)              { return __hip_atomic_load(p, __ATOMIC_RELAXED, __HIP_MEMORY_SCOPE_AGENT); }
; __device__ __forceinline__ unsigned xb_add(unsigned* p, unsigned v) { return __hip_atomic_fetch_add(p, v, __ATOMIC_RELAXED, __HIP_MEMORY_SCOPE_AGENT); }
; #define XB_SPIN(cond, bar) do { unsigned _sp = 0; while (cond) { __builtin_amdgcn_s_sleep(1); \
;     if ((++_sp & 255u) == 0u) { if (xb_ld(&(bar)[XB_TMO])) break; if (_sp > XB_SPIN_CAP) { atomicAdd(&(bar)[XB_TMO], 1u); break; } } } } while (0)
; __device__ __forceinline__ void xcd_barrier(const XcdBarrier& b) {
;     asm volatile("s_waitcnt vmcnt(0)" ::: "memory");
;     __syncthreads();
;     if (threadIdx.x == 0) {
;         unsigned* bar = b.bar;
;         __builtin_amdgcn_s_waitcnt(0);
;         unsigned nloc = b.st[0], nx = b.st[1];
;         if (nloc == 0u) { xcd_barrier_complete(bar, b.x, nloc, nx); b.st[0] = nloc; b.st[1] = nx; }
;         const unsigned old = xb_add(&bar[XB_XSUB(b.x)], 1u);
;         const unsigned gen = old / nloc;
;         if (old + 1u == (gen + 1u) * nloc) {
;             __builtin_amdgcn_fence(__ATOMIC_RELEASE, "agent");
;             asm volatile("s_waitcnt vmcnt(0)" ::: "memory");
;             const unsigned og = xb_add(&bar[XB_TOP], 1u);
;             const unsigned tg = og / nx;
;             if (og + 1u == (tg + 1u) * nx) xb_add(&bar[XB_TOPGEN], 1u);
;             else XB_SPIN(xb_ld(&bar[XB_TOPGEN]) == tg, bar);
;             __builtin_amdgcn_fence(__ATOMIC_ACQUIRE, "agent");
;             xb_add(&bar[XB_XGEN(b.x)], 1u);
;             asm volatile("s_waitcnt vmcnt(0)" ::: "memory");
;         } else {
;             XB_SPIN(xb_ld(&bar[XB_XGEN(b.x)]) == gen, bar);
;             __builtin_amdgcn_fence(__ATOMIC_ACQUIRE, "agent");
;             asm volatile("s_waitcnt vmcnt(0)" ::: "memory");
;         }
;     }
;     __syncthreads();
; }
.LBB0_818:
	s_cmp_gt_i32 s31, 7
	s_cselect_b64 s[0:1], -1, 0
	s_and_b64 s[4:5], s[4:5], s[0:1]
	v_readlane_b32 s68, v254, 8
	v_readlane_b32 s70, v254, 6
	v_readlane_b32 s76, v254, 4
	s_andn2_b64 vcc, exec, s[4:5]
	v_readlane_b32 s69, v254, 9
	v_readlane_b32 s71, v254, 7
	v_readlane_b32 s77, v254, 5
	s_cbranch_vccnz .LBB0_868
	s_waitcnt vmcnt(0)
	s_barrier
	v_cmp_eq_u32_e32 vcc, 0, v195
	s_and_saveexec_b64 s[4:5], vcc
	s_cbranch_execz .Ltb868_done
	s_cmp_eq_u32 s99, 1
	s_cbranch_scc1 .Ltb868_fast
	buffer_wbl2 sc1
	s_waitcnt vmcnt(0)

;     __host__ __device__ bool next(int i, Unit& u) const {
;         const long L = (long)i * G + c; if (L >= nwg) return false;
;         int wgid = (int)L; { const int q = nwg / NXCD, r = nwg % NXCD, xcd = wgid % NXCD, off = wgid / NXCD; wgid = (xcd < r ? xcd * (q + 1) : r * (q + 1) + (xcd - r) * q) + off; }
;         const int nig = WGM * nN, gid = wgid / nig, fm = gid * WGM, gsz = (nM % WGM == 0) ? WGM : ((nM - fm) < WGM ? (nM - fm) : WGM);
;         u.pm = fm + ((wgid % nig) % gsz); u.pn = (wgid % nig) / gsz; return true;
; __global__ void __launch_bounds__(NWAVES * 64, 2) mk_fwd(Args a) {
;     ...
;     if (IN(7)) { pg8::Gemm g{S2, WO, M, D, D}; pg8::StaticOrder S; S.init(M, D, G, bid); EpiN<0, false, false, true> E{S3, nullptr, nullptr, PART};
;         pg8::gemm_phase<EpiN<0, false, false, true>, pg8::StaticOrder, true, true, NT_NARROW, ZZ, PEELK>(lds, g, S, E); }
.Ltb868_done:
	s_or_b64 exec, exec, s[4:5]
	s_barrier
.LBB0_868:
	s_cmp_lt_i32 s30, 8
	s_cselect_b64 s[4:5], -1, 0
	s_and_b64 s[4:5], s[4:5], s[0:1]
	s_andn2_b64 vcc, exec, s[4:5]
	s_cbranch_vccnz .LBB0_893
	s_cmpk_gt_i32 s2, 0x1ff
	v_readfirstlane_b32 s6, v195
	s_cbranch_scc1 .LBB0_893
	s_ashr_i32 s3, s2, 31
	s_lshr_b32 s0, s3, 29
	s_add_i32 s8, s2, s0
	s_and_b32 s0, s8, -8
	s_sub_i32 s9, s2, s0
	s_cmp_gt_i32 s9, -1
	s_cbranch_scc0 .LBB0_872
	s_lshl_b32 s7, s9, 6
	s_cbranch_execz .LBB0_873
	s_branch .LBB0_874

; __device__ __forceinline__ unsigned xb_ld(unsigned* p)              { return __hip_atomic_load(p, __ATOMIC_RELAXED, __HIP_MEMORY_SCOPE_AGENT); }
; __device__ __forceinline__ unsigned xb_add(unsigned* p, unsigned v) { return __hip_atomic_fetch_add(p, v, __ATOMIC_RELAXED, __HIP_MEMORY_SCOPE_AGENT); }
; #define XB_SPIN(cond, bar) do { unsigned _sp = 0; while (cond) { __builtin_amdgcn_s_sleep(1); \
;     if ((++_sp & 255u) == 0u) { if (xb_ld(&(bar)[XB_TMO])) break; if (_sp > XB_SPIN_CAP) { atomicAdd(&(bar)[XB_TMO], 1u); break; } } } } while (0)
; __device__ __forceinline__ void xcd_barrier(const XcdBarrier& b) {
;     asm volatile("s_waitcnt vmcnt(0)" ::: "memory");
;     __syncthreads();
;     if (threadIdx.x == 0) {
;         unsigned* bar = b.bar;
;         __builtin_amdgcn_s_waitcnt(0);
;         unsigned nloc = b.st[0], nx = b.st[1];
;         if (nloc == 0u) { xcd_barrier_complete(bar, b.x, nloc, nx); b.st[0] = nloc; b.st[1] = nx; }
;         const unsigned old = xb_add(&bar[XB_XSUB(b.x)], 1u);
;         const unsigned gen = old / nloc;
;         if (old + 1u == (gen + 1u) * nloc) {
;             __builtin_amdgcn_fence(__ATOMIC_RELEASE, "agent");
;             asm volatile("s_waitcnt vmcnt(0)" ::: "memory");
;             const unsigned og = xb_add(&bar[XB_TOP], 1u);
;             const unsigned tg = og / nx;
;             if (og + 1u == (tg + 1u) * nx) xb_add(&bar[XB_TOPGEN], 1u);
;             else XB_SPIN(xb_ld(&bar[XB_TOPGEN]) == tg, bar);
;             __builtin_amdgcn_fence(__ATOMIC_ACQUIRE, "agent");
;             xb_add(&bar[XB_XGEN(b.x)], 1u);
;             asm volatile("s_waitcnt vmcnt(0)" ::: "memory");
;         } else {
;             XB_SPIN(xb_ld(&bar[XB_XGEN(b.x)]) == gen, bar);
;             __builtin_amdgcn_fence(__ATOMIC_ACQUIRE, "agent");
;             asm volatile("s_waitcnt vmcnt(0)" ::: "memory");
;         }
;     }
;     __syncthreads();
; }
.LBB0_1084:
	s_cmp_gt_i32 s31, 10
	s_cselect_b64 s[0:1], -1, 0
	s_and_b64 s[4:5], s[6:7], s[0:1]
	s_andn2_b64 vcc, exec, s[4:5]
	s_cbranch_vccnz .LBB0_1134
	s_waitcnt vmcnt(0)
	s_barrier
	v_cmp_eq_u32_e32 vcc, 0, v195
	s_and_saveexec_b64 s[4:5], vcc
	s_cbranch_execz .Ltb1134_done
	s_cmp_eq_u32 s99, 1
	s_cbranch_scc1 .Ltb1134_fast
	buffer_wbl2 sc1
	s_waitcnt vmcnt(0)

;     __host__ __device__ bool next(int i, Unit& u) const {
;         const long L = (long)i * G + c; if (L >= nwg) return false;
;         int wgid = (int)L; { const int q = nwg / NXCD, r = nwg % NXCD, xcd = wgid % NXCD, off = wgid / NXCD; wgid = (xcd < r ? xcd * (q + 1) : r * (q + 1) + (xcd - r) * q) + off; }
;         const int nig = WGM * nN, gid = wgid / nig, fm = gid * WGM, gsz = (nM % WGM == 0) ? WGM : ((nM - fm) < WGM ? (nM - fm) : WGM);
;         u.pm = fm + ((wgid % nig) % gsz); u.pn = (wgid % nig) / gsz; return true;
; __global__ void __launch_bounds__(NWAVES * 64, 2) mk_fwd(Args a) {
;     ...
;     if (IN(10)) { pg8::Gemm g{ACT, WD2, M, D, FF}; pg8::StaticOrder S; S.init(M, D, G, bid); EpiN<0, false, false, true> E{FB, nullptr, nullptr, PART};
;         pg8::gemm_phase<EpiN<0, false, false, true>, pg8::StaticOrder, true, true, NT_NARROW, ZZ, PEELK>(lds, g, S, E); }
.Ltb1134_done:
	s_or_b64 exec, exec, s[4:5]
	s_barrier
.LBB0_1134:
	s_cmp_lt_i32 s30, 11
	s_cselect_b64 s[4:5], -1, 0
	s_and_b64 s[6:7], s[4:5], s[0:1]
	s_andn2_b64 vcc, exec, s[6:7]
	s_cbranch_vccnz .LBB0_1163
	s_cmpk_gt_i32 s2, 0x1ff
	v_readfirstlane_b32 s4, v195
	s_cbranch_scc1 .LBB0_1163
	s_ashr_i32 s3, s2, 31
	s_lshr_b32 s0, s3, 29
	s_add_i32 s5, s2, s0
	s_and_b32 s0, s5, -8
	s_sub_i32 s9, s2, s0
	s_cmp_gt_i32 s9, -1
	s_cbranch_scc0 .LBB0_1138
	s_lshl_b32 s8, s9, 6
	s_cbranch_execz .LBB0_1139
	s_branch .LBB0_1140

; __global__ void __launch_bounds__(NWAVES * 64, 2) mk_fwd(Args a) {
	.amdhsa_kernel _Z6mk_fwd4Args
		.amdhsa_group_segment_fixed_size 0
		.amdhsa_private_segment_fixed_size 0
		.amdhsa_kernarg_size 496
		.amdhsa_user_sgpr_count 2
		.amdhsa_user_sgpr_dispatch_ptr 0
		.amdhsa_user_sgpr_queue_ptr 0
		.amdhsa_user_sgpr_kernarg_segment_ptr 1
		.amdhsa_user_sgpr_dispatch_id 0
		.amdhsa_user_sgpr_kernarg_preload_length 0
		.amdhsa_user_sgpr_kernarg_preload_offset 0
		.amdhsa_user_sgpr_private_segment_size 0
		.amdhsa_uses_dynamic_stack 0
		.amdhsa_enable_private_segment 0
		.amdhsa_system_sgpr_workgroup_id_x 1
		.amdhsa_system_sgpr_workgroup_id_y 0
		.amdhsa_system_sgpr_workgroup_id_z 0
		.amdhsa_system_sgpr_workgroup_info 0
		.amdhsa_system_vgpr_workitem_id 2
		.amdhsa_next_free_vgpr 255
		.amdhsa_next_free_sgpr 102
		.amdhsa_accum_offset 256
		.amdhsa_reserve_vcc 1
		.amdhsa_float_round_mode_32 0
		.amdhsa_float_round_mode_16_64 0
		.amdhsa_float_denorm_mode_32 3
		.amdhsa_float_denorm_mode_16_64 3
		.amdhsa_dx10_clamp 1
		.amdhsa_ieee_mode 1
		.amdhsa_fp16_overflow 0
		.amdhsa_tg_split 0
		.amdhsa_exception_fp_ieee_invalid_op 0
		.amdhsa_exception_fp_denorm_src 0
		.amdhsa_exception_fp_ieee_div_zero 0
		.amdhsa_exception_fp_ieee_overflow 0
		.amdhsa_exception_fp_ieee_underflow 0
		.amdhsa_exception_fp_ieee_inexact 0
		.amdhsa_exception_int_div_zero 0
	.end_amdhsa_kernel

; __global__ void __launch_bounds__(NWAVES * 64, 2) mk_fwd(Args a) {
amdhsa.kernels:
  - .agpr_count:     0
    .args:
      - .offset:         0
        .size:           240
        .value_kind:     by_value
      - .offset:         240
        .size:           4
        .value_kind:     hidden_block_count_x
      - .offset:         244
        .size:           4
        .value_kind:     hidden_block_count_y
      - .offset:         248
        .size:           4
        .value_kind:     hidden_block_count_z
      - .offset:         252
        .size:           2
        .value_kind:     hidden_group_size_x
      - .offset:         254
        .size:           2
        .value_kind:     hidden_group_size_y
      - .offset:         256
        .size:           2
        .value_kind:     hidden_group_size_z
      - .offset:         258
        .size:           2
        .value_kind:     hidden_remainder_x
      - .offset:         260
        .size:           2
        .value_kind:     hidden_remainder_y
      - .offset:         262
        .size:           2
        .value_kind:     hidden_remainder_z
      - .offset:         280
        .size:           8
        .value_kind:     hidden_global_offset_x
      - .offset:         288
        .size:           8
        .value_kind:     hidden_global_offset_y
      - .offset:         296
        .size:           8
        .value_kind:     hidden_global_offset_z
      - .offset:         304
        .size:           2
        .value_kind:     hidden_grid_dims
      - .offset:         328
        .size:           8
        .value_kind:     hidden_multigrid_sync_arg
      - .offset:         360
        .size:           4
        .value_kind:     hidden_dynamic_lds_size
    .group_segment_fixed_size: 0
    .kernarg_segment_align: 8
    .kernarg_segment_size: 496
    .language:       OpenCL C
    .language_version:
      - 2
      - 0
    .max_flat_workgroup_size: 512
    .name:           _Z6mk_fwd4Args
    .private_segment_fixed_size: 0
    .sgpr_count:     108
    .sgpr_spill_count: 56
    .symbol:         _Z6mk_fwd4Args.kd
    .uniform_work_group_size: 1
    .uses_dynamic_stack: false
    .vgpr_count:     255
    .vgpr_spill_count: 0
    .wavefront_size: 64
